# post_row: loop-invariant gain loads hoisted out of the row loop; plus all previous
# speedup vs baseline: 1.0561x; 1.0048x over previous
.LBB0_252:
	s_and_b64 vcc, exec, s[0:1]
	s_cbranch_vccz .LBB0_256
	s_mov_b32 s0, -1
	s_nop 0
	v_mbcnt_lo_u32_b32 v0, s0, 0
	v_mbcnt_hi_u32_b32 v0, s0, v0
	v_readlane_b32 s0, v250, 25
	s_nop 1
	v_add_u32_e32 v4, s0, v0
	v_readlane_b32 s0, v250, 38
	v_readlane_b32 s1, v250, 39
	s_andn2_b64 vcc, exec, s[0:1]
	s_cbranch_vccnz .LBB0_256
	s_waitcnt lgkmcnt(0)
	v_and_b32_e32 v1, 64, v178
	v_xor_b32_e32 v0, 1, v178
	v_add_u32_e32 v1, 64, v1
	v_cmp_lt_i32_e32 vcc, v0, v1
	v_and_b32_e32 v2, 63, v4
	v_readlane_b32 s0, v254, 16
	v_cndmask_b32_e32 v0, v178, v0, vcc
	v_lshlrev_b32_e32 v22, 2, v0
	v_xor_b32_e32 v0, 2, v178
	v_cmp_lt_i32_e32 vcc, v0, v1
	v_lshlrev_b32_e32 v6, 4, v2
	v_lshlrev_b32_e32 v2, 5, v2
	v_cndmask_b32_e32 v0, v178, v0, vcc
	v_lshlrev_b32_e32 v23, 2, v0
	v_xor_b32_e32 v0, 4, v178
	v_cmp_lt_i32_e32 vcc, v0, v1
	v_mov_b32_e32 v3, v64
	v_readlane_b32 s1, v254, 17
	v_cndmask_b32_e32 v0, v178, v0, vcc
	v_lshlrev_b32_e32 v24, 2, v0
	v_lshlrev_b32_e32 v0, 6, v4
	v_lshl_add_u64 v[2:3], s[0:1], 0, v[2:3]
	v_lshrrev_b32_e32 v4, 2, v4
	v_readlane_b32 s0, v254, 57
	v_and_b32_e32 v4, 12, v4
	v_mov_b32_e32 v5, v64
	v_readlane_b32 s1, v254, 58
	v_mov_b32_e32 v7, v64
	v_readlane_b32 s52, v254, 36
	v_lshl_add_u64 v[4:5], s[0:1], 0, v[4:5]
	v_readlane_b32 s0, v254, 27
	v_readlane_b32 s1, v254, 28
	v_and_b32_e32 v0, 0x1c0, v0
	v_mov_b32_e32 v1, v64
	v_readlane_b32 s66, v254, 50
	v_readlane_b32 s67, v254, 51
	v_lshl_add_u64 v[6:7], s[0:1], 0, v[6:7]
	v_readlane_b32 s0, v254, 55
	v_readlane_b32 s4, v254, 20
	v_lshl_add_u64 v[0:1], s[66:67], 0, v[0:1]
	s_mov_b32 s2, s0
	v_readlane_b32 s5, v254, 21
	v_readlane_b32 s53, v254, 37
	v_readlane_b32 s54, v254, 38
	v_readlane_b32 s55, v254, 39
	v_readlane_b32 s56, v254, 40
	v_readlane_b32 s57, v254, 41
	v_readlane_b32 s58, v254, 42
	v_readlane_b32 s59, v254, 43
	v_readlane_b32 s60, v254, 44
	v_readlane_b32 s61, v254, 45
	v_readlane_b32 s62, v254, 46
	v_readlane_b32 s63, v254, 47
	v_readlane_b32 s64, v254, 48
	v_readlane_b32 s65, v254, 49
	v_readlane_b32 s1, v254, 56
	global_load_dwordx4 v[92:95], v[0:1], off
	global_load_dwordx4 v[96:99], v[0:1], off offset:16
	global_load_dwordx4 v[100:103], v[0:1], off offset:32
	global_load_dwordx4 v[104:107], v[0:1], off offset:48
.LBB0_255:
	v_lshl_add_u64 v[8:9], s[90:91], 0, v[6:7]
	s_mov_b32 s0, 0x11000000
	v_add_co_u32_e64 v12, s[0:1], s0, v8
	v_lshl_add_u64 v[10:11], s[8:9], 0, v[2:3]
	s_nop 0
	v_addc_co_u32_e64 v13, s[0:1], 0, v9, s[0:1]
	s_brev_b32 s0, 40
	s_nop 0
	v_add_co_u32_e64 v28, s[0:1], s0, v8
	v_lshl_add_u64 v[26:27], s[90:91], 0, v[2:3]
	s_nop 0
	v_addc_co_u32_e64 v29, s[0:1], 0, v9, s[0:1]
	s_mov_b32 s0, 0x17000000
	s_nop 0
	v_add_co_u32_e64 v30, s[0:1], s0, v8
	v_lshl_add_u64 v[34:35], s[90:91], 0, v[4:5]
	s_nop 0
	v_addc_co_u32_e64 v31, s[0:1], 0, v9, s[0:1]
	s_mov_b64 s[0:1], 0x2000000
	s_nop 0
	v_lshl_add_u64 v[16:17], v[10:11], 0, s[0:1]
	v_add_co_u32_e64 v14, s[0:1], s3, v10
	v_add_co_u32_e32 v34, vcc, 0x3f00000, v34
	s_nop 0
	v_addc_co_u32_e64 v15, s[0:1], 0, v11, s[0:1]
	s_mov_b64 s[0:1], 0xf000000
	s_nop 0
	v_lshl_add_u64 v[18:19], v[26:27], 0, s[0:1]
	s_mov_b32 s0, 0xf000000
	v_add_co_u32_e64 v20, s[0:1], s0, v26
	v_addc_co_u32_e32 v35, vcc, 0, v35, vcc
	s_nop 0
	v_addc_co_u32_e64 v21, s[0:1], 0, v27, s[0:1]
	s_mov_b32 s0, 0x5000000
	s_nop 0
	v_add_co_u32_e64 v8, s[0:1], s0, v26
	s_add_i32 s2, s2, s96
	s_nop 0
	v_addc_co_u32_e64 v9, s[0:1], 0, v27, s[0:1]
	global_load_dwordx4 v[26:29], v[28:29], off
	s_nop 0
	global_load_dwordx4 v[30:33], v[30:31], off
	s_nop 0
	global_load_dword v25, v[34:35], off
	global_load_dword v54, v[34:35], off offset:16
	global_load_dword v55, v[34:35], off offset:32
	s_nop 0
	global_load_dwordx4 v[34:37], v[12:13], off
	v_lshl_add_u64 v[2:3], v[2:3], 0, s[4:5]
	v_lshl_add_u64 v[4:5], v[4:5], 0, s[18:19]
	v_lshl_add_u64 v[6:7], v[6:7], 0, s[48:49]
	s_cmpk_gt_i32 s2, 0x3fff
	s_waitcnt vmcnt(0)
	v_lshlrev_b32_e32 v41, 16, v27
	s_waitcnt vmcnt(1)
	v_max3_f32 v56, v25, v54, v55
	s_waitcnt vmcnt(0)
	v_lshlrev_b32_e32 v40, 16, v34
	v_and_b32_e32 v44, 0xffff0000, v34
	v_sub_f32_e32 v25, v25, v56
	v_sub_f32_e32 v34, v54, v56
	v_and_b32_e32 v45, 0xffff0000, v27
	v_lshlrev_b32_e32 v39, 16, v35
	v_and_b32_e32 v27, 0xffff0000, v35
	v_lshlrev_b32_e32 v48, 16, v36
	v_and_b32_e32 v52, 0xffff0000, v36
	v_sub_f32_e32 v36, v55, v56
	v_exp_f32_e32 v35, v25
	v_exp_f32_e32 v34, v34
	v_exp_f32_e32 v25, v36
	v_lshlrev_b32_e32 v49, 16, v29
	v_and_b32_e32 v53, 0xffff0000, v29
	v_add_f32_e32 v36, v35, v34
	v_add_f32_e32 v36, v25, v36
	v_lshlrev_b32_e32 v47, 16, v37
	v_and_b32_e32 v29, 0xffff0000, v37
	v_div_scale_f32 v37, s[0:1], v36, v36, 1.0
	v_rcp_f32_e32 v55, v37
	v_div_scale_f32 v54, vcc, 1.0, v36, 1.0
	v_lshlrev_b32_e32 v38, 16, v26
	v_fma_f32 v56, -v37, v55, 1.0
	v_fmac_f32_e32 v55, v56, v55
	v_mul_f32_e32 v56, v54, v55
	v_fma_f32 v57, -v37, v56, v54
	v_fmac_f32_e32 v56, v57, v55
	v_fma_f32 v37, -v37, v56, v54
	v_div_fmas_f32 v37, v37, v55, v56
	v_div_fixup_f32 v36, v37, v36, 1.0
	v_pk_mul_f32 v[34:35], v[34:35], v[36:37] op_sel_hi:[1,0]
	v_and_b32_e32 v26, 0xffff0000, v26
	v_lshlrev_b32_e32 v46, 16, v28
	v_and_b32_e32 v28, 0xffff0000, v28
	v_mul_f32_e32 v54, v25, v36
	v_pk_mul_f32 v[36:37], v[34:35], v[40:41] op_sel:[1,0] op_sel_hi:[0,1]
	v_pk_mul_f32 v[40:41], v[34:35], v[44:45] op_sel:[1,0] op_sel_hi:[0,1]
	v_pk_mul_f32 v[44:45], v[34:35], v[48:49] op_sel:[1,0] op_sel_hi:[0,1]
	v_pk_mul_f32 v[48:49], v[34:35], v[52:53] op_sel:[1,0] op_sel_hi:[0,1]
	v_lshlrev_b32_e32 v43, 16, v31
	v_lshlrev_b32_e32 v42, 16, v30
	v_and_b32_e32 v31, 0xffff0000, v31
	v_and_b32_e32 v30, 0xffff0000, v30
	v_lshlrev_b32_e32 v51, 16, v33
	v_lshlrev_b32_e32 v50, 16, v32
	v_and_b32_e32 v33, 0xffff0000, v33
	v_and_b32_e32 v32, 0xffff0000, v32
	v_pk_fma_f32 v[36:37], v[34:35], v[38:39], v[36:37]
	v_pk_fma_f32 v[26:27], v[34:35], v[26:27], v[40:41]
	v_pk_fma_f32 v[38:39], v[34:35], v[46:47], v[44:45]
	v_pk_fma_f32 v[28:29], v[34:35], v[28:29], v[48:49]
	v_pk_fma_f32 v[34:35], v[54:55], v[42:43], v[36:37] op_sel_hi:[0,1,1]
	v_pk_fma_f32 v[26:27], v[54:55], v[30:31], v[26:27] op_sel_hi:[0,1,1]
	v_pk_fma_f32 v[30:31], v[54:55], v[50:51], v[38:39] op_sel_hi:[0,1,1]
	v_pk_fma_f32 v[28:29], v[54:55], v[32:33], v[28:29] op_sel_hi:[0,1,1]
	v_bfe_u32 v25, v29, 16, 1
	v_bfe_u32 v32, v28, 16, 1
	v_bfe_u32 v37, v34, 16, 1
	v_bfe_u32 v38, v35, 16, 1
	v_bfe_u32 v39, v30, 16, 1
	v_bfe_u32 v40, v31, 16, 1
	v_bfe_u32 v33, v27, 16, 1
	v_bfe_u32 v36, v26, 16, 1
	v_add3_u32 v28, v28, v32, s6
	v_add3_u32 v25, v29, v25, s6
	v_add3_u32 v29, v31, v40, s6
	v_add3_u32 v30, v30, v39, s6
	v_add3_u32 v31, v35, v38, s6
	v_add3_u32 v32, v34, v37, s6
	v_add3_u32 v26, v26, v36, s6
	v_add3_u32 v27, v27, v33, s6
	v_lshrrev_b32_e32 v32, 16, v32
	v_lshrrev_b32_e32 v31, 16, v31
	v_lshrrev_b32_e32 v30, 16, v30
	v_lshrrev_b32_e32 v29, 16, v29
	v_and_or_b32 v29, v25, s7, v29
	v_and_or_b32 v28, v28, s7, v30
	v_and_or_b32 v27, v27, s7, v31
	v_and_or_b32 v26, v26, s7, v32
	global_store_dwordx4 v[12:13], v[26:29], off
	global_load_dwordx4 v[26:29], v[10:11], off offset:16
	s_nop 0
	global_load_dwordx4 v[30:33], v[16:17], off offset:16
	s_nop 0
	global_load_dwordx4 v[10:13], v[10:11], off
	s_nop 0
	global_load_dwordx4 v[14:17], v[14:15], off
	s_nop 0
	global_load_dwordx4 v[38:41], v[20:21], off
	s_nop 0
	global_load_dwordx4 v[18:21], v[18:19], off offset:16
	s_waitcnt vmcnt(5)
	v_and_b32_e32 v46, 0xffff0000, v28
	v_lshlrev_b32_e32 v47, 16, v28
	s_waitcnt vmcnt(4)
	v_and_b32_e32 v48, 0xffff0000, v32
	v_lshlrev_b32_e32 v49, 16, v32
	v_and_b32_e32 v28, 0xffff0000, v29
	v_lshlrev_b32_e32 v29, 16, v29
	v_and_b32_e32 v32, 0xffff0000, v33
	v_lshlrev_b32_e32 v33, 16, v33
	s_waitcnt vmcnt(3)
	v_lshlrev_b32_e32 v51, 16, v11
	v_lshlrev_b32_e32 v50, 16, v10
	s_waitcnt vmcnt(2)
	v_lshlrev_b32_e32 v53, 16, v15
	v_lshlrev_b32_e32 v52, 16, v14
	v_and_b32_e32 v11, 0xffff0000, v11
	v_and_b32_e32 v10, 0xffff0000, v10
	v_and_b32_e32 v15, 0xffff0000, v15
	v_and_b32_e32 v14, 0xffff0000, v14
	v_mov_b32_e32 v34, v92
	v_mov_b32_e32 v35, v93
	v_mov_b32_e32 v36, v94
	v_mov_b32_e32 v37, v95
	v_mov_b32_e32 v54, v34
	v_mov_b32_e32 v55, v36
	s_waitcnt vmcnt(1)
	v_lshlrev_b32_e32 v57, 16, v39
	v_lshlrev_b32_e32 v56, 16, v38
	v_mov_b32_e32 v36, v35
	v_and_b32_e32 v35, 0xffff0000, v39
	v_and_b32_e32 v34, 0xffff0000, v38
	v_lshlrev_b32_e32 v39, 16, v13
	v_lshlrev_b32_e32 v38, 16, v12
	v_lshlrev_b32_e32 v59, 16, v17
	v_lshlrev_b32_e32 v58, 16, v16
	v_mov_b32_e32 v42, v96
	v_mov_b32_e32 v43, v97
	v_mov_b32_e32 v44, v98
	v_mov_b32_e32 v45, v99
	v_mov_b32_e32 v60, v42
	v_mov_b32_e32 v61, v44
	v_mov_b32_e32 v44, v43
	v_lshlrev_b32_e32 v43, 16, v27
	v_lshlrev_b32_e32 v42, 16, v26
	v_lshlrev_b32_e32 v67, 16, v31
	v_lshlrev_b32_e32 v66, 16, v30
	v_pk_add_f32 v[28:29], v[28:29], v[32:33]
	v_pk_add_f32 v[32:33], v[50:51], v[52:53]
	v_pk_add_f32 v[10:11], v[10:11], v[14:15]
	v_pk_add_f32 v[46:47], v[46:47], v[48:49]
	v_pk_add_f32 v[14:15], v[38:39], v[58:59]
	v_pk_add_f32 v[38:39], v[42:43], v[66:67]
	v_pk_mul_f32 v[42:43], v[32:33], v[32:33]
	v_pk_mul_f32 v[48:49], v[10:11], v[10:11]
	v_and_b32_e32 v13, 0xffff0000, v13
	v_add_f32_e32 v25, v42, v48
	v_and_b32_e32 v12, 0xffff0000, v12
	v_and_b32_e32 v17, 0xffff0000, v17
	v_and_b32_e32 v16, 0xffff0000, v16
	v_add_f32_e32 v25, v43, v25
	v_pk_add_f32 v[12:13], v[12:13], v[16:17]
	v_pk_mul_f32 v[50:51], v[14:15], v[14:15]
	v_add_f32_e32 v25, v49, v25
	v_and_b32_e32 v27, 0xffff0000, v27
	v_and_b32_e32 v26, 0xffff0000, v26
	v_and_b32_e32 v31, 0xffff0000, v31
	v_and_b32_e32 v30, 0xffff0000, v30
	v_pk_mul_f32 v[52:53], v[12:13], v[12:13]
	v_add_f32_e32 v25, v50, v25
	v_pk_add_f32 v[26:27], v[26:27], v[30:31]
	v_add_f32_e32 v25, v52, v25
	v_mov_b32_e32 v58, v26
	v_mov_b32_e32 v59, v38
	v_add_f32_e32 v25, v51, v25
	v_pk_mul_f32 v[58:59], v[58:59], v[58:59]
	v_add_f32_e32 v25, v53, v25
	v_mov_b32_e32 v66, v27
	v_mov_b32_e32 v67, v39
	v_add_f32_e32 v25, v59, v25
	v_pk_mul_f32 v[66:67], v[66:67], v[66:67]
	v_add_f32_e32 v25, v58, v25
	v_add_f32_e32 v25, v67, v25
	v_pk_mul_f32 v[16:17], v[46:47], v[46:47]
	v_add_f32_e32 v25, v66, v25
	v_add_f32_e32 v17, v17, v25
	v_pk_mul_f32 v[30:31], v[28:29], v[28:29]
	v_add_f32_e32 v16, v16, v17
	v_add_f32_e32 v16, v31, v16
	v_add_f32_e32 v16, v30, v16
	ds_bpermute_b32 v17, v22, v16
	v_lshlrev_b32_e32 v63, 16, v41
	v_lshlrev_b32_e32 v62, 16, v40
	v_and_b32_e32 v41, 0xffff0000, v41
	v_and_b32_e32 v40, 0xffff0000, v40
	s_waitcnt lgkmcnt(0)
	v_add_f32_e32 v16, v16, v17
	ds_bpermute_b32 v17, v23, v16
	s_waitcnt lgkmcnt(0)
	v_add_f32_e32 v16, v16, v17
	ds_bpermute_b32 v17, v24, v16
	s_waitcnt lgkmcnt(0)
	v_add_f32_e32 v16, v16, v17
	v_fmamk_f32 v16, v16, 0x3c000000, v176
	v_mul_f32_e32 v17, 0x4b800000, v16
	v_cmp_gt_f32_e32 vcc, s11, v16
	s_nop 1
	v_cndmask_b32_e32 v16, v16, v17, vcc
	v_rsq_f32_e32 v16, v16
	s_nop 0
	v_mul_f32_e32 v17, 0x45800000, v16
	v_cndmask_b32_e32 v30, v16, v17, vcc
	v_pk_mul_f32 v[16:17], v[32:33], v[30:31] op_sel_hi:[1,0]
	v_pk_mul_f32 v[14:15], v[14:15], v[30:31] op_sel_hi:[1,0]
	v_pk_mul_f32 v[10:11], v[10:11], v[30:31] op_sel_hi:[1,0]
	v_pk_mul_f32 v[12:13], v[12:13], v[30:31] op_sel_hi:[1,0]
	v_pk_mul_f32 v[16:17], v[54:55], v[16:17]
	v_pk_mul_f32 v[14:15], v[60:61], v[14:15]
	v_pk_mul_f32 v[10:11], v[36:37], v[10:11]
	v_pk_mul_f32 v[12:13], v[44:45], v[12:13]
	v_pk_mul_f32 v[16:17], v[16:17], v[56:57]
	v_pk_mul_f32 v[14:15], v[14:15], v[62:63]
	v_pk_mul_f32 v[10:11], v[10:11], v[34:35]
	v_pk_mul_f32 v[12:13], v[12:13], v[40:41]
	v_bfe_u32 v34, v16, 16, 1
	v_bfe_u32 v35, v17, 16, 1
	v_bfe_u32 v36, v14, 16, 1
	v_bfe_u32 v37, v15, 16, 1
	v_bfe_u32 v25, v13, 16, 1
	v_bfe_u32 v31, v12, 16, 1
	v_bfe_u32 v32, v11, 16, 1
	v_bfe_u32 v33, v10, 16, 1
	v_add3_u32 v15, v15, v37, s6
	v_add3_u32 v14, v14, v36, s6
	v_add3_u32 v17, v17, v35, s6
	v_add3_u32 v16, v16, v34, s6
	v_add3_u32 v10, v10, v33, s6
	v_add3_u32 v11, v11, v32, s6
	v_add3_u32 v12, v12, v31, s6
	v_add3_u32 v13, v13, v25, s6
	v_lshrrev_b32_e32 v16, 16, v16
	v_lshrrev_b32_e32 v17, 16, v17
	v_lshrrev_b32_e32 v14, 16, v14
	v_lshrrev_b32_e32 v15, 16, v15
	v_and_or_b32 v13, v13, s7, v15
	v_and_or_b32 v12, v12, s7, v14
	v_and_or_b32 v11, v11, s7, v17
	v_and_or_b32 v10, v10, s7, v16
	global_store_dwordx4 v[8:9], v[10:13], off
	s_nop 0
	v_mov_b32_e32 v36, v47
	v_mov_b32_e32 v37, v29
	v_mov_b32_e32 v47, v28
	v_pk_mul_f32 v[28:29], v[38:39], v[30:31] op_sel_hi:[1,0]
	v_pk_mul_f32 v[36:37], v[36:37], v[30:31] op_sel_hi:[1,0]
	s_waitcnt vmcnt(1)
	v_lshlrev_b32_e32 v33, 16, v19
	v_lshlrev_b32_e32 v32, 16, v18
	v_lshlrev_b32_e32 v35, 16, v21
	v_lshlrev_b32_e32 v34, 16, v20
	v_pk_mul_f32 v[26:27], v[26:27], v[30:31] op_sel_hi:[1,0]
	v_pk_mul_f32 v[30:31], v[46:47], v[30:31] op_sel_hi:[1,0]
	v_and_b32_e32 v19, 0xffff0000, v19
	v_and_b32_e32 v18, 0xffff0000, v18
	v_and_b32_e32 v21, 0xffff0000, v21
	v_and_b32_e32 v20, 0xffff0000, v20
	v_mov_b32_e32 v10, v100
	v_mov_b32_e32 v11, v101
	v_mov_b32_e32 v12, v102
	v_mov_b32_e32 v13, v103
	v_mov_b32_e32 v38, v10
	v_mov_b32_e32 v39, v12
	v_mov_b32_e32 v12, v11
	v_mov_b32_e32 v14, v104
	v_mov_b32_e32 v15, v105
	v_mov_b32_e32 v16, v106
	v_mov_b32_e32 v17, v107
	v_mov_b32_e32 v10, v14
	v_mov_b32_e32 v11, v16
	v_mov_b32_e32 v16, v15
	v_pk_mul_f32 v[14:15], v[38:39], v[28:29]
	v_pk_mul_f32 v[10:11], v[10:11], v[36:37]
	v_pk_mul_f32 v[12:13], v[12:13], v[26:27]
	v_pk_mul_f32 v[16:17], v[16:17], v[30:31]
	v_pk_mul_f32 v[14:15], v[14:15], v[32:33]
	v_pk_mul_f32 v[10:11], v[10:11], v[34:35]
	v_pk_mul_f32 v[12:13], v[12:13], v[18:19]
	v_pk_mul_f32 v[16:17], v[16:17], v[20:21]
	v_bfe_u32 v25, v14, 16, 1
	v_bfe_u32 v26, v15, 16, 1
	v_bfe_u32 v27, v10, 16, 1
	v_bfe_u32 v28, v11, 16, 1
	v_bfe_u32 v18, v17, 16, 1
	v_bfe_u32 v19, v16, 16, 1
	v_bfe_u32 v20, v13, 16, 1
	v_bfe_u32 v21, v12, 16, 1
	v_add3_u32 v11, v11, v28, s6
	v_add3_u32 v10, v10, v27, s6
	v_add3_u32 v15, v15, v26, s6
	v_add3_u32 v14, v14, v25, s6
	v_add3_u32 v21, v12, v21, s6
	v_add3_u32 v20, v13, v20, s6
	v_add3_u32 v12, v16, v19, s6
	v_add3_u32 v13, v17, v18, s6
	v_lshrrev_b32_e32 v14, 16, v14
	v_lshrrev_b32_e32 v15, 16, v15
	v_lshrrev_b32_e32 v10, 16, v10
	v_lshrrev_b32_e32 v11, 16, v11
	v_and_or_b32 v13, v13, s7, v11
	v_and_or_b32 v12, v12, s7, v10
	v_and_or_b32 v11, v20, s7, v15
	v_and_or_b32 v10, v21, s7, v14
	global_store_dwordx4 v[8:9], v[10:13], off offset:16
	s_cbranch_scc0 .LBB0_255
